# phase-1 prepass (x -> bf16 modulated H + row ssq): per-row 4 serialized load/compute chunks replaced by a rolling one-row-ahead prefetch with counted waits; flat stores -> global stores
# baseline (speedup 1.0000x reference)
; __device__ __forceinline__ int otid() { int t = (int)threadIdx.x; asm volatile("" : "+v"(t)); return t; }
; __device__ __forceinline__ int obid() { int b = (int)blockIdx.x; asm volatile("" : "+s"(b)); return b; }
; __device__ __forceinline__ unsigned cvt_pk_bf16(float lo, float hi) { unsigned r; asm volatile("v_cvt_pk_bf16_f32 %0, %1, %2" : "=v"(r) : "v"(lo), "v"(hi)); return r; }
; __device__ __forceinline__ void prepass_phase(const float* xin, const float* g, const float* mod  , int sc_off, bf16_t* XG, float* ssq, int G) {
;     const int tid = otid(), lane = tid & 63, wid = __builtin_amdgcn_readfirstlane(tid >> 6);
;     for (int m = obid() * NWAVES + wid; m < NTOK; m += G * NWAVES) {
;         const f32x4* xr = (const f32x4*)(xin + (size_t)m * DM) + lane; float s = 0.f;
;         const float* mb = mod + (size_t)(m >> 12) * 6144;
; #pragma unroll
;         for (int j = 0; j < 4; ++j) { const f32x4 v = xr[64 * j]; s += (v[0] * v[0] + v[1] * v[1]) + (v[2] * v[2] + v[3] * v[3]); const int col = 4 * lane + 256 * j;
;             const f32x4 o = v * *(const f32x4*)(g + col) * (1.0f + *(const f32x4*)(mb + sc_off + col));
;             u32x2 w; w.x = cvt_pk_bf16(o[0], o[1]); w.y = cvt_pk_bf16(o[2], o[3]);
;             *(u32x2*)(XG + (size_t)m * DM + col) = w; }
;         s = wave_sum(s);
;         if (lane == 0) ssq[m] = s;
;     }
.LBB0_659:
	v_mov_b32_e32 v0, v221
	v_readlane_b32 s3, v254, 0
	s_waitcnt vmcnt(0) lgkmcnt(0)
	s_barrier
	s_lshl_b32 s3, s3, 3
	v_readfirstlane_b32 s2, v0
	s_ashr_i32 s2, s2, 6
	s_add_i32 s2, s3, s2
	s_cmp_gt_i32 s2, 0xffff
	s_cbranch_scc1 .LBB0_664
	v_readlane_b32 s6, v255, 29
	v_readlane_b32 s7, v255, 30
	s_load_dwordx2 s[4:5], s[6:7], 0x0
	s_load_dwordx2 s[8:9], s[6:7], 0x20
	v_and_b32_e32 v4, 63, v0
	v_readlane_b32 s3, v255, 28
	s_lshl_b32 s6, s3, 3
	v_lshlrev_b32_e32 v0, 4, v4
	s_ashr_i32 s3, s2, 31
	s_waitcnt lgkmcnt(0)
	v_lshl_add_u64 v[2:3], s[8:9], 0, v[0:1]
	s_lshl_b64 s[8:9], s[2:3], 2
	s_add_u32 s7, s92, s8
	s_addc_u32 s9, s93, s9
	s_add_u32 s8, s7, 0x3e680000
	s_addc_u32 s9, s9, 0
	s_ashr_i32 s7, s6, 31
	s_lshl_b64 s[10:11], s[6:7], 2
	s_lshl_b64 s[12:13], s[2:3], 11
	s_add_u32 s12, s92, s12
	v_lshlrev_b32_e32 v8, 2, v4
	v_cmp_eq_u32_e32 vcc, 0, v4
	v_lshlrev_b32_e32 v4, 3, v4
	v_mov_b32_e32 v5, v1
	s_addc_u32 s13, s93, s13
	v_lshl_add_u64 v[4:5], s[12:13], 0, v[4:5]
	s_lshl_b64 s[12:13], s[6:7], 11
	s_lshl_b64 s[14:15], s[2:3], 12
	s_add_u32 s4, s4, s14
	s_addc_u32 s5, s5, s15
	v_or_b32_e32 v10, 0x100, v8
	v_or_b32_e32 v12, 0x200, v8
	v_or_b32_e32 v14, 0x300, v8
	v_lshl_add_u64 v[6:7], s[4:5], 0, v[0:1]
	v_lshl_add_u64 v[6:7], v[6:7], 0, s[88:89]
	s_lshl_b64 s[14:15], s[6:7], 12
	v_lshlrev_b32_e32 v0, 2, v8
	v_lshlrev_b32_e32 v8, 2, v10
	v_lshlrev_b32_e32 v9, 2, v12
	v_lshlrev_b32_e32 v10, 2, v14
	global_load_dwordx4 v[12:15], v[2:3], off
	global_load_dwordx4 v[16:19], v[2:3], off offset:1024
	global_load_dwordx4 v[20:23], v[2:3], off offset:2048
	global_load_dwordx4 v[24:27], v[2:3], off offset:3072
	v_xor_b32_e32 v28, 1, v228
	v_xor_b32_e32 v29, 2, v228
	v_xor_b32_e32 v30, 4, v228
	v_xor_b32_e32 v31, 8, v228
	v_xor_b32_e32 v32, 16, v228
	v_xor_b32_e32 v33, 32, v228
	v_lshlrev_b32_e32 v28, 2, v28
	v_lshlrev_b32_e32 v29, 2, v29
	v_lshlrev_b32_e32 v30, 2, v30
	v_lshlrev_b32_e32 v31, 2, v31
	v_lshlrev_b32_e32 v32, 2, v32
	v_lshlrev_b32_e32 v33, 2, v33
	s_ashr_i32 s3, s2, 12
	s_mul_hi_i32 s4, s3, 0x6000
	s_mulk_i32 s3, 0x6000
	s_add_u32 s3, s92, s3
	s_addc_u32 s4, s93, s4
	s_add_u32 s16, s3, 0x3dc01000
	s_addc_u32 s17, s4, 0
	global_load_dwordx4 v[178:181], v[6:7], off offset:-2048
	global_load_dwordx4 v[162:165], v0, s[16:17]
	global_load_dwordx4 v[182:185], v[6:7], off offset:-1024
	global_load_dwordx4 v[166:169], v8, s[16:17]
	global_load_dwordx4 v[186:189], v[6:7], off
	global_load_dwordx4 v[170:173], v9, s[16:17]
	global_load_dwordx4 v[190:193], v[6:7], off offset:1024
	global_load_dwordx4 v[174:177], v10, s[16:17]
	s_waitcnt vmcnt(0)
.Lprepass_row:
	s_add_i32 s3, s2, s6
	s_cmp_gt_i32 s3, 0xffff
	s_cselect_b32 s3, s2, s3
	s_cselect_b32 s100, 0, s14
	s_cselect_b32 s101, 0, s15
	v_lshl_add_u64 v[210:211], v[6:7], 0, s[100:101]
	s_ashr_i32 s3, s3, 12
	s_mul_hi_i32 s4, s3, 0x6000
	s_mulk_i32 s3, 0x6000
	s_add_u32 s3, s92, s3
	s_addc_u32 s4, s93, s4
	s_add_u32 s16, s3, 0x3dc01000
	s_addc_u32 s17, s4, 0
	s_waitcnt vmcnt(10)
	v_pk_mul_f32 v[34:35], v[178:179], v[12:13]
	v_pk_add_f32 v[162:163], v[162:163], 1.0 op_sel_hi:[1,0]
	v_pk_mul_f32 v[36:37], v[180:181], v[14:15]
	v_pk_add_f32 v[164:165], v[164:165], 1.0 op_sel_hi:[1,0]
	v_pk_mul_f32 v[34:35], v[34:35], v[162:163]
	v_pk_mul_f32 v[36:37], v[36:37], v[164:165]
	v_cvt_pk_bf16_f32 v38, v34, v35
	v_cvt_pk_bf16_f32 v39, v36, v37
	v_mul_f32_e32 v212, v179, v179
	v_mul_f32_e32 v213, v181, v181
	v_fmac_f32_e32 v212, v178, v178
	v_fmac_f32_e32 v213, v180, v180
	v_add_f32_e32 v214, v212, v213
	global_store_dwordx2 v[4:5], v[38:39], off
	global_load_dwordx4 v[178:181], v[210:211], off offset:-2048
	global_load_dwordx4 v[162:165], v0, s[16:17]
	s_waitcnt vmcnt(10)
	v_pk_mul_f32 v[34:35], v[182:183], v[16:17]
	v_pk_add_f32 v[166:167], v[166:167], 1.0 op_sel_hi:[1,0]
	v_pk_mul_f32 v[36:37], v[184:185], v[18:19]
	v_pk_add_f32 v[168:169], v[168:169], 1.0 op_sel_hi:[1,0]
	v_pk_mul_f32 v[34:35], v[34:35], v[166:167]
	v_pk_mul_f32 v[36:37], v[36:37], v[168:169]
	v_cvt_pk_bf16_f32 v38, v34, v35
	v_cvt_pk_bf16_f32 v39, v36, v37
	v_mul_f32_e32 v212, v183, v183
	v_mul_f32_e32 v213, v185, v185
	v_fmac_f32_e32 v212, v182, v182
	v_fmac_f32_e32 v213, v184, v184
	v_add_f32_e32 v212, v212, v213
	v_add_f32_e32 v214, v214, v212
	global_store_dwordx2 v[4:5], v[38:39], off offset:512
	global_load_dwordx4 v[182:185], v[210:211], off offset:-1024
	global_load_dwordx4 v[166:169], v8, s[16:17]
	s_waitcnt vmcnt(10)
	v_pk_mul_f32 v[34:35], v[186:187], v[20:21]
	v_pk_add_f32 v[170:171], v[170:171], 1.0 op_sel_hi:[1,0]
	v_pk_mul_f32 v[36:37], v[188:189], v[22:23]
	v_pk_add_f32 v[172:173], v[172:173], 1.0 op_sel_hi:[1,0]
	v_pk_mul_f32 v[34:35], v[34:35], v[170:171]
	v_pk_mul_f32 v[36:37], v[36:37], v[172:173]
	v_cvt_pk_bf16_f32 v38, v34, v35
	v_cvt_pk_bf16_f32 v39, v36, v37
	v_mul_f32_e32 v212, v187, v187
	v_mul_f32_e32 v213, v189, v189
	v_fmac_f32_e32 v212, v186, v186
	v_fmac_f32_e32 v213, v188, v188
	v_add_f32_e32 v212, v212, v213
	v_add_f32_e32 v214, v214, v212
	global_store_dwordx2 v[4:5], v[38:39], off offset:1024
	global_load_dwordx4 v[186:189], v[210:211], off
	global_load_dwordx4 v[170:173], v9, s[16:17]
	s_waitcnt vmcnt(10)
	v_pk_mul_f32 v[34:35], v[190:191], v[24:25]
	v_pk_add_f32 v[174:175], v[174:175], 1.0 op_sel_hi:[1,0]
	v_pk_mul_f32 v[36:37], v[192:193], v[26:27]
	v_pk_add_f32 v[176:177], v[176:177], 1.0 op_sel_hi:[1,0]
	v_pk_mul_f32 v[34:35], v[34:35], v[174:175]
	v_pk_mul_f32 v[36:37], v[36:37], v[176:177]
	v_cvt_pk_bf16_f32 v38, v34, v35
	v_cvt_pk_bf16_f32 v39, v36, v37
	v_mul_f32_e32 v212, v191, v191
	v_mul_f32_e32 v213, v193, v193
	v_fmac_f32_e32 v212, v190, v190
	v_fmac_f32_e32 v213, v192, v192
	v_add_f32_e32 v212, v212, v213
	v_add_f32_e32 v214, v214, v212
	global_store_dwordx2 v[4:5], v[38:39], off offset:1536
	global_load_dwordx4 v[190:193], v[210:211], off offset:1024
	global_load_dwordx4 v[174:177], v10, s[16:17]
	ds_bpermute_b32 v215, v28, v214
	s_waitcnt lgkmcnt(0)
	v_add_f32_e32 v214, v214, v215
	ds_bpermute_b32 v215, v29, v214
	s_waitcnt lgkmcnt(0)
	v_add_f32_e32 v214, v214, v215
	ds_bpermute_b32 v215, v30, v214
	s_waitcnt lgkmcnt(0)
	v_add_f32_e32 v214, v214, v215
	ds_bpermute_b32 v215, v31, v214
	s_waitcnt lgkmcnt(0)
	v_add_f32_e32 v214, v214, v215
	ds_bpermute_b32 v215, v32, v214
	s_waitcnt lgkmcnt(0)
	v_add_f32_e32 v214, v214, v215
	ds_bpermute_b32 v215, v33, v214
	s_waitcnt lgkmcnt(0)
	v_add_f32_e32 v214, v214, v215
	s_and_saveexec_b64 s[40:41], vcc
	global_store_dword v1, v214, s[8:9]
	s_or_b64 exec, exec, s[40:41]
	s_add_i32 s2, s2, s6
	s_add_u32 s8, s8, s10
	s_addc_u32 s9, s9, s11
	v_lshl_add_u64 v[4:5], v[4:5], 0, s[12:13]
	v_lshl_add_u64 v[6:7], v[6:7], 0, s[14:15]
	s_cmp_gt_i32 s2, 0xffff
	s_cbranch_scc0 .Lprepass_row
	s_waitcnt vmcnt(0)
